# abin GEMM k-loop on the 3-stage LDS-DMA ring with fragment double buffering (was hipcc's register-staged loop)
# speedup vs baseline: 1.0149x; 1.0077x over previous
.LBB0_861:
	s_ashr_i32 s0, s49, 31
	s_lshr_b32 s0, s0, 27
	s_add_i32 s0, s49, s0
	s_and_b32 s1, s0, 0xffffe0
	s_sub_i32 s1, s49, s1
	s_lshl_b32 s0, s0, 2
	s_lshl_b32 s20, s1, 8
	s_and_b32 s0, s0, 0xffffff80
	s_ashr_i32 s21, s20, 31
	s_ashr_i32 s1, s0, 31
	v_readlane_b32 s4, v254, 0
	s_lshl_b64 s[22:23], s[20:21], 11
	s_lshl_b64 s[24:25], s[0:1], 11
	v_readlane_b32 s6, v254, 2
	v_readlane_b32 s7, v254, 3
	s_add_u32 s22, s6, s22
	s_addc_u32 s23, s7, s23
	s_add_u32 s24, s50, s24
	s_addc_u32 s25, s51, s25
	s_waitcnt lgkmcnt(0)
	v_lshlrev_b32_e32 v176, 1, v125
	v_lshrrev_b32_e32 v174, 3, v196
	v_lshrrev_b32_e32 v175, 4, v196
	v_xor_b32_e32 v175, v175, v196
	v_and_b32_e32 v175, 7, v175
	v_lshlrev_b32_e32 v175, 4, v175
	v_lshl_or_b32 v162, v174, 11, v175
	v_add_u32_e32 v163, 0x20000, v162
	v_add_u32_e32 v164, 0x40000, v162
	v_add_u32_e32 v165, 0x60000, v162
	v_add_u32_e32 v174, 0, v105
	v_xor_b32_e32 v174, v174, v122
	v_lshlrev_b32_e32 v174, 4, v174
	v_add3_u32 v166, v126, v174, 16
	v_add3_u32 v170, v176, v174, 16
	v_add_u32_e32 v174, 2, v105
	v_xor_b32_e32 v174, v174, v122
	v_lshlrev_b32_e32 v174, 4, v174
	v_add3_u32 v167, v126, v174, 16
	v_add3_u32 v171, v176, v174, 16
	v_add_u32_e32 v174, 4, v105
	v_xor_b32_e32 v174, v174, v122
	v_lshlrev_b32_e32 v174, 4, v174
	v_add3_u32 v168, v126, v174, 16
	v_add3_u32 v172, v176, v174, 16
	v_add_u32_e32 v174, 6, v105
	v_xor_b32_e32 v174, v174, v122
	v_lshlrev_b32_e32 v174, 4, v174
	v_add3_u32 v169, v126, v174, 16
	v_add3_u32 v173, v176, v174, 16
	v_lshrrev_b32_e32 v174, 6, v196
	v_mov_b64_e32 v[16:17], 0
	v_mov_b64_e32 v[18:19], 0
	v_mov_b64_e32 v[20:21], 0
	v_mov_b64_e32 v[22:23], 0
	v_mov_b64_e32 v[24:25], 0
	v_mov_b64_e32 v[26:27], 0
	v_mov_b64_e32 v[28:29], 0
	v_mov_b64_e32 v[30:31], 0
	v_mov_b64_e32 v[32:33], 0
	v_mov_b64_e32 v[34:35], 0
	v_mov_b64_e32 v[36:37], 0
	v_mov_b64_e32 v[38:39], 0
	v_mov_b64_e32 v[40:41], 0
	v_mov_b64_e32 v[42:43], 0
	v_mov_b64_e32 v[44:45], 0
	v_mov_b64_e32 v[46:47], 0
	v_mov_b64_e32 v[48:49], 0
	v_mov_b64_e32 v[50:51], 0
	v_mov_b64_e32 v[52:53], 0
	v_mov_b64_e32 v[54:55], 0
	v_mov_b64_e32 v[56:57], 0
	v_mov_b64_e32 v[58:59], 0
	v_mov_b64_e32 v[60:61], 0
	v_mov_b64_e32 v[62:63], 0
	v_mov_b64_e32 v[64:65], 0
	v_mov_b64_e32 v[66:67], 0
	v_mov_b64_e32 v[68:69], 0
	v_mov_b64_e32 v[70:71], 0
	v_mov_b64_e32 v[72:73], 0
	v_mov_b64_e32 v[74:75], 0
	v_mov_b64_e32 v[76:77], 0
	v_mov_b64_e32 v[78:79], 0
	v_readfirstlane_b32 s27, v174
	s_lshl_b32 s27, s27, 10
	s_add_i32 s27, s27, 16
	s_add_i32 vcc_hi, s27, 0xc000
	s_mov_b32 m0, s27
	s_nop 0
	global_load_lds_dwordx4 v162, s[22:23]
	s_add_u32 m0, m0, 0x2000
	s_nop 0
	global_load_lds_dwordx4 v163, s[22:23]
	s_add_u32 m0, m0, 0x2000
	s_nop 0
	global_load_lds_dwordx4 v164, s[22:23]
	s_add_u32 m0, m0, 0x2000
	s_nop 0
	global_load_lds_dwordx4 v165, s[22:23]
	s_add_u32 m0, m0, 0x2000
	s_nop 0
	global_load_lds_dwordx4 v162, s[24:25]
	s_add_u32 m0, m0, 0x2000
	s_nop 0
	global_load_lds_dwordx4 v163, s[24:25]
	s_add_u32 s22, s22, 0x80
	s_addc_u32 s23, s23, 0
	s_add_u32 s24, s24, 0x80
	s_addc_u32 s25, s25, 0
	s_mov_b32 m0, vcc_hi
	s_nop 0
	global_load_lds_dwordx4 v162, s[22:23]
	s_add_u32 m0, m0, 0x2000
	s_nop 0
	global_load_lds_dwordx4 v163, s[22:23]
	s_add_u32 m0, m0, 0x2000
	s_nop 0
	global_load_lds_dwordx4 v164, s[22:23]
	s_add_u32 m0, m0, 0x2000
	s_nop 0
	global_load_lds_dwordx4 v165, s[22:23]
	s_add_u32 m0, m0, 0x2000
	s_nop 0
	global_load_lds_dwordx4 v162, s[24:25]
	s_add_u32 m0, m0, 0x2000
	s_nop 0
	global_load_lds_dwordx4 v163, s[24:25]
	s_add_u32 s22, s22, 0x80
	s_addc_u32 s23, s23, 0
	s_add_u32 s24, s24, 0x80
	s_addc_u32 s25, s25, 0
	s_mov_b32 s26, 0
	s_movk_i32 s21, 14
.Labin_loop:
	s_waitcnt vmcnt(6)
	s_barrier
	s_add_i32 vcc_hi, s26, 2
	s_cmp_ge_u32 vcc_hi, 3
	s_cselect_b32 vcc_lo, 3, 0
	s_sub_i32 vcc_hi, vcc_hi, vcc_lo
	s_mul_i32 vcc_hi, vcc_hi, 0xc000
	s_add_i32 vcc_hi, vcc_hi, s27
	ds_read_b128 v[4:7], v166
	ds_read_b128 v[8:11], v166 offset:4096
	ds_read_b128 v[12:15], v170 offset:32768
	ds_read_b128 v[142:145], v170 offset:36864
	ds_read_b128 v[146:149], v167
	ds_read_b128 v[150:153], v167 offset:4096
	ds_read_b128 v[154:157], v171 offset:32768
	ds_read_b128 v[158:161], v171 offset:36864
	s_waitcnt lgkmcnt(4)
	s_setprio 1
	v_mfma_f32_32x32x16_bf16 v[32:47], v[4:7], v[12:15], v[32:47]
	s_mov_b32 m0, vcc_hi
	v_mfma_f32_32x32x16_bf16 v[16:31], v[8:11], v[12:15], v[16:31]
	global_load_lds_dwordx4 v162, s[22:23]
	s_add_u32 m0, m0, 0x2000
	v_mfma_f32_32x32x16_bf16 v[48:63], v[4:7], v[142:145], v[48:63]
	global_load_lds_dwordx4 v163, s[22:23]
	s_add_u32 m0, m0, 0x2000
	v_mfma_f32_32x32x16_bf16 v[64:79], v[8:11], v[142:145], v[64:79]
	global_load_lds_dwordx4 v164, s[22:23]
	s_add_u32 m0, m0, 0x2000
	s_nop 0
	global_load_lds_dwordx4 v165, s[22:23]
	s_add_u32 m0, m0, 0x2000
	s_nop 0
	global_load_lds_dwordx4 v162, s[24:25]
	s_add_u32 m0, m0, 0x2000
	s_nop 0
	global_load_lds_dwordx4 v163, s[24:25]
	s_add_u32 s22, s22, 0x80
	s_addc_u32 s23, s23, 0
	s_add_u32 s24, s24, 0x80
	s_addc_u32 s25, s25, 0
	s_setprio 0
	ds_read_b128 v[4:7], v168
	ds_read_b128 v[8:11], v168 offset:4096
	ds_read_b128 v[12:15], v172 offset:32768
	ds_read_b128 v[142:145], v172 offset:36864
	s_waitcnt lgkmcnt(4)
	s_setprio 1
	v_mfma_f32_32x32x16_bf16 v[32:47], v[146:149], v[154:157], v[32:47]
	v_mfma_f32_32x32x16_bf16 v[16:31], v[150:153], v[154:157], v[16:31]
	v_mfma_f32_32x32x16_bf16 v[48:63], v[146:149], v[158:161], v[48:63]
	v_mfma_f32_32x32x16_bf16 v[64:79], v[150:153], v[158:161], v[64:79]
	s_setprio 0
	ds_read_b128 v[146:149], v169
	ds_read_b128 v[150:153], v169 offset:4096
	ds_read_b128 v[154:157], v173 offset:32768
	ds_read_b128 v[158:161], v173 offset:36864
	s_waitcnt lgkmcnt(4)
	s_setprio 1
	v_mfma_f32_32x32x16_bf16 v[32:47], v[4:7], v[12:15], v[32:47]
	v_mfma_f32_32x32x16_bf16 v[16:31], v[8:11], v[12:15], v[16:31]
	v_mfma_f32_32x32x16_bf16 v[48:63], v[4:7], v[142:145], v[48:63]
	v_mfma_f32_32x32x16_bf16 v[64:79], v[8:11], v[142:145], v[64:79]
	s_setprio 0
	s_waitcnt lgkmcnt(0)
	s_setprio 1
	v_mfma_f32_32x32x16_bf16 v[32:47], v[146:149], v[154:157], v[32:47]
	v_mfma_f32_32x32x16_bf16 v[16:31], v[150:153], v[154:157], v[16:31]
	v_mfma_f32_32x32x16_bf16 v[48:63], v[146:149], v[158:161], v[48:63]
	v_mfma_f32_32x32x16_bf16 v[64:79], v[150:153], v[158:161], v[64:79]
	s_setprio 0
	s_add_i32 s26, s26, 1
	s_cmp_eq_u32 s26, 3
	s_cselect_b32 vcc_lo, 0xfffdc000, 0
	s_cselect_b32 s26, 0, s26
	s_add_i32 vcc_lo, vcc_lo, 0xc000
	v_add_u32_e32 v166, vcc_lo, v166
	v_add_u32_e32 v170, vcc_lo, v170
	v_add_u32_e32 v167, vcc_lo, v167
	v_add_u32_e32 v171, vcc_lo, v171
	v_add_u32_e32 v168, vcc_lo, v168
	v_add_u32_e32 v172, vcc_lo, v172
	v_add_u32_e32 v169, vcc_lo, v169
	v_add_u32_e32 v173, vcc_lo, v173
	s_add_i32 s21, s21, -1
	s_cmp_lg_u32 s21, 0
	s_cbranch_scc1 .Labin_loop
	s_waitcnt vmcnt(6)
	s_barrier
	ds_read_b128 v[4:7], v166
	ds_read_b128 v[8:11], v166 offset:4096
	ds_read_b128 v[12:15], v170 offset:32768
	ds_read_b128 v[142:145], v170 offset:36864
	ds_read_b128 v[146:149], v167
	ds_read_b128 v[150:153], v167 offset:4096
	ds_read_b128 v[154:157], v171 offset:32768
	ds_read_b128 v[158:161], v171 offset:36864
	s_waitcnt lgkmcnt(4)
	s_setprio 1
	v_mfma_f32_32x32x16_bf16 v[32:47], v[4:7], v[12:15], v[32:47]
	v_mfma_f32_32x32x16_bf16 v[16:31], v[8:11], v[12:15], v[16:31]
	v_mfma_f32_32x32x16_bf16 v[48:63], v[4:7], v[142:145], v[48:63]
	v_mfma_f32_32x32x16_bf16 v[64:79], v[8:11], v[142:145], v[64:79]
	s_setprio 0
	ds_read_b128 v[4:7], v168
	ds_read_b128 v[8:11], v168 offset:4096
	ds_read_b128 v[12:15], v172 offset:32768
	ds_read_b128 v[142:145], v172 offset:36864
	s_waitcnt lgkmcnt(4)
	s_setprio 1
	v_mfma_f32_32x32x16_bf16 v[32:47], v[146:149], v[154:157], v[32:47]
	v_mfma_f32_32x32x16_bf16 v[16:31], v[150:153], v[154:157], v[16:31]
	v_mfma_f32_32x32x16_bf16 v[48:63], v[146:149], v[158:161], v[48:63]
	v_mfma_f32_32x32x16_bf16 v[64:79], v[150:153], v[158:161], v[64:79]
	s_setprio 0
	ds_read_b128 v[146:149], v169
	ds_read_b128 v[150:153], v169 offset:4096
	ds_read_b128 v[154:157], v173 offset:32768
	ds_read_b128 v[158:161], v173 offset:36864
	s_waitcnt lgkmcnt(4)
	s_setprio 1
	v_mfma_f32_32x32x16_bf16 v[32:47], v[4:7], v[12:15], v[32:47]
	v_mfma_f32_32x32x16_bf16 v[16:31], v[8:11], v[12:15], v[16:31]
	v_mfma_f32_32x32x16_bf16 v[48:63], v[4:7], v[142:145], v[48:63]
	v_mfma_f32_32x32x16_bf16 v[64:79], v[8:11], v[142:145], v[64:79]
	s_setprio 0
	s_waitcnt lgkmcnt(0)
	s_setprio 1
	v_mfma_f32_32x32x16_bf16 v[32:47], v[146:149], v[154:157], v[32:47]
	v_mfma_f32_32x32x16_bf16 v[16:31], v[150:153], v[154:157], v[16:31]
	v_mfma_f32_32x32x16_bf16 v[48:63], v[146:149], v[158:161], v[48:63]
	v_mfma_f32_32x32x16_bf16 v[64:79], v[150:153], v[158:161], v[64:79]
	s_setprio 0
	s_add_i32 s26, s26, 1
	s_cmp_eq_u32 s26, 3
	s_cselect_b32 vcc_lo, 0xfffdc000, 0
	s_cselect_b32 s26, 0, s26
	s_add_i32 vcc_lo, vcc_lo, 0xc000
	v_add_u32_e32 v166, vcc_lo, v166
	v_add_u32_e32 v170, vcc_lo, v170
	v_add_u32_e32 v167, vcc_lo, v167
	v_add_u32_e32 v171, vcc_lo, v171
	v_add_u32_e32 v168, vcc_lo, v168
	v_add_u32_e32 v172, vcc_lo, v172
	v_add_u32_e32 v169, vcc_lo, v169
	v_add_u32_e32 v173, vcc_lo, v173
	s_waitcnt vmcnt(0)
	s_barrier
	ds_read_b128 v[4:7], v166
	ds_read_b128 v[8:11], v166 offset:4096
	ds_read_b128 v[12:15], v170 offset:32768
	ds_read_b128 v[142:145], v170 offset:36864
	ds_read_b128 v[146:149], v167
	ds_read_b128 v[150:153], v167 offset:4096
	ds_read_b128 v[154:157], v171 offset:32768
	ds_read_b128 v[158:161], v171 offset:36864
	s_waitcnt lgkmcnt(4)
	s_setprio 1
	v_mfma_f32_32x32x16_bf16 v[32:47], v[4:7], v[12:15], v[32:47]
	v_mfma_f32_32x32x16_bf16 v[16:31], v[8:11], v[12:15], v[16:31]
	v_mfma_f32_32x32x16_bf16 v[48:63], v[4:7], v[142:145], v[48:63]
	v_mfma_f32_32x32x16_bf16 v[64:79], v[8:11], v[142:145], v[64:79]
	s_setprio 0
	ds_read_b128 v[4:7], v168
	ds_read_b128 v[8:11], v168 offset:4096
	ds_read_b128 v[12:15], v172 offset:32768
	ds_read_b128 v[142:145], v172 offset:36864
	s_waitcnt lgkmcnt(4)
	s_setprio 1
	v_mfma_f32_32x32x16_bf16 v[32:47], v[146:149], v[154:157], v[32:47]
	v_mfma_f32_32x32x16_bf16 v[16:31], v[150:153], v[154:157], v[16:31]
	v_mfma_f32_32x32x16_bf16 v[48:63], v[146:149], v[158:161], v[48:63]
	v_mfma_f32_32x32x16_bf16 v[64:79], v[150:153], v[158:161], v[64:79]
	s_setprio 0
	ds_read_b128 v[146:149], v169
	ds_read_b128 v[150:153], v169 offset:4096
	ds_read_b128 v[154:157], v173 offset:32768
	ds_read_b128 v[158:161], v173 offset:36864
	s_waitcnt lgkmcnt(4)
	s_setprio 1
	v_mfma_f32_32x32x16_bf16 v[32:47], v[4:7], v[12:15], v[32:47]
	v_mfma_f32_32x32x16_bf16 v[16:31], v[8:11], v[12:15], v[16:31]
	v_mfma_f32_32x32x16_bf16 v[48:63], v[4:7], v[142:145], v[48:63]
	v_mfma_f32_32x32x16_bf16 v[64:79], v[8:11], v[142:145], v[64:79]
	s_setprio 0
	s_waitcnt lgkmcnt(0)
	s_setprio 1
	v_mfma_f32_32x32x16_bf16 v[32:47], v[146:149], v[154:157], v[32:47]
	v_mfma_f32_32x32x16_bf16 v[16:31], v[150:153], v[154:157], v[16:31]
	v_mfma_f32_32x32x16_bf16 v[48:63], v[146:149], v[158:161], v[48:63]
	v_mfma_f32_32x32x16_bf16 v[64:79], v[150:153], v[158:161], v[64:79]
	s_setprio 0
	s_barrier
	v_mov_b32_e32 v0, v1
	v_readlane_b32 s4, v254, 0
	v_readlane_b32 s5, v254, 1
	v_readlane_b32 s6, v254, 2
	v_readlane_b32 s7, v254, 3
	v_readlane_b32 s8, v254, 4
	v_readlane_b32 s9, v254, 5
	v_readlane_b32 s10, v254, 6
	v_readlane_b32 s11, v254, 7
	v_readlane_b32 s12, v254, 8
	v_readlane_b32 s13, v254, 9
	v_readlane_b32 s14, v254, 10
	v_readlane_b32 s15, v254, 11
	v_readlane_b32 s16, v254, 12
	v_readlane_b32 s17, v254, 13
	v_readlane_b32 s18, v254, 14
	v_readlane_b32 s19, v254, 15
	s_nop 7
	v_add_u32_e32 v2, s20, v123
	s_movk_i32 s1, 0x1000
	v_cmp_gt_i32_e64 s[42:43], s1, v2
	v_add_u32_e32 v3, 0xfffff000, v2
	s_movk_i32 s1, 0xfff
	v_lshrrev_b32_e32 v3, 11, v3
	v_ashrrev_i32_e32 v10, 8, v2
	v_cmp_lt_i32_e64 s[44:45], s1, v2
	ds_write2_b32 v141, v32, v48 offset1:32
	ds_write2_b32 v141, v33, v49 offset0:65 offset1:97
	ds_write2_b32 v141, v34, v50 offset0:130 offset1:162
	ds_write2_b32 v141, v35, v51 offset0:195 offset1:227
	v_cndmask_b32_e64 v9, v10, v3, s[44:45]
	v_and_b32_e32 v3, 0x7c0, v2
	v_cndmask_b32_e64 v8, v127, v3, s[44:45]
	v_add_u32_e32 v3, 0x800, v141
	ds_write2_b32 v3, v36, v52 offset0:8 offset1:40
	ds_write2_b32 v3, v37, v53 offset0:73 offset1:105
	ds_write2_b32 v3, v38, v54 offset0:138 offset1:170
	ds_write2_b32 v3, v39, v55 offset0:203 offset1:235
	v_add_u32_e32 v3, 0x1000, v141
	ds_write2_b32 v3, v40, v56 offset0:16 offset1:48
	ds_write2_b32 v3, v41, v57 offset0:81 offset1:113
	ds_write2_b32 v3, v42, v58 offset0:146 offset1:178
	ds_write2_b32 v3, v43, v59 offset0:211 offset1:243
	v_add_u32_e32 v3, 0x1800, v141
	ds_write2_b32 v3, v44, v60 offset0:24 offset1:56
	ds_write2_b32 v3, v45, v61 offset0:89 offset1:121
	ds_write2_b32 v3, v46, v62 offset0:154 offset1:186
	ds_write2_b32 v3, v47, v63 offset0:219 offset1:251
	v_add_u32_e32 v3, 0x2000, v141
	ds_write2_b32 v3, v16, v64 offset0:32 offset1:64
	ds_write2_b32 v3, v17, v65 offset0:97 offset1:129
	ds_write2_b32 v3, v18, v66 offset0:162 offset1:194
	v_add_u32_e32 v3, 0x2200, v141
	ds_write2_b32 v3, v19, v67 offset0:99 offset1:131
	v_add_u32_e32 v3, 0x2800, v141
	ds_write2_b32 v3, v20, v68 offset0:40 offset1:72
	ds_write2_b32 v3, v21, v69 offset0:105 offset1:137
	ds_write2_b32 v3, v22, v70 offset0:170 offset1:202
	v_add_u32_e32 v3, 0x2a00, v141
	ds_write2_b32 v3, v23, v71 offset0:107 offset1:139
	v_add_u32_e32 v3, 0x3000, v141
	ds_write2_b32 v3, v24, v72 offset0:48 offset1:80
	ds_write2_b32 v3, v25, v73 offset0:113 offset1:145
	ds_write2_b32 v3, v26, v74 offset0:178 offset1:210
	v_add_u32_e32 v3, 0x3200, v141
	v_or_b32_e32 v0, s0, v124
	s_movk_i32 s1, 0x3ff
	ds_write2_b32 v3, v27, v75 offset0:115 offset1:147
	v_add_u32_e32 v3, 0x3800, v141
	v_cmp_lt_i32_e32 vcc, s1, v0
	ds_write2_b32 v3, v28, v76 offset0:56 offset1:88
	ds_write2_b32 v3, v29, v77 offset0:121 offset1:153
	ds_write2_b32 v3, v30, v78 offset0:186 offset1:218
	v_add_u32_e32 v3, 0x3a00, v141
	ds_write2_b32 v3, v31, v79 offset0:123 offset1:155
	s_waitcnt lgkmcnt(0)
	s_barrier
	s_and_saveexec_b64 s[20:21], vcc
	s_xor_b64 s[28:29], exec, s[20:21]
	s_cbranch_execz .LBB0_880
	s_cmpk_gt_u32 s0, 0x5ff
	s_mov_b64 s[0:1], -1
	s_cbranch_scc0 .LBB0_873
	v_readlane_b32 s4, v253, 46
	v_readlane_b32 s12, v253, 54
	v_readlane_b32 s13, v253, 55
	s_movk_i32 s0, 0x1c00
	s_mov_b32 s20, 1
	v_mov_b64_e32 v[4:5], s[12:13]
	v_mad_i64_i32 v[2:3], s[0:1], v2, s0, v[4:5]
	v_lshl_add_u64 v[2:3], v[0:1], 2, v[2:3]
	v_lshlrev_b32_e32 v4, 2, v104
	v_mov_b32_e32 v5, v1
	s_movk_i32 s0, 0xe800
	v_lshl_add_u64 v[2:3], v[2:3], 0, v[4:5]
	s_mov_b32 s1, -1
	v_lshl_add_u64 v[2:3], v[2:3], 0, s[0:1]
	s_mov_b32 s21, 0
	s_mov_b32 s22, 64
	v_readlane_b32 s5, v253, 47
	v_readlane_b32 s6, v253, 48
	v_readlane_b32 s7, v253, 49
	v_readlane_b32 s8, v253, 50
	v_readlane_b32 s9, v253, 51
	v_readlane_b32 s10, v253, 52
	v_readlane_b32 s11, v253, 53
	v_readlane_b32 s14, v253, 56
	v_readlane_b32 s15, v253, 57
	v_readlane_b32 s16, v253, 58
	v_readlane_b32 s17, v253, 59
	v_readlane_b32 s18, v253, 60
	v_readlane_b32 s19, v253, 61
